# GEMM K loops: no s_setprio at all (flat priority)
# speedup vs baseline: 1.0032x; 1.0032x over previous
.LBB0_1023:
	v_readfirstlane_b32 s98, v246
	s_cmpk_ge_u32 s98, 0x100
	s_cbranch_scc0 .Lsp_skip_1024
